# removed the grid barrier between the independent phases 12 and 13 (layer-1 weight transpose -> layer-1 norm)
# speedup vs baseline: 1.0025x; 1.0025x over previous
; __global__ void __launch_bounds__(512, 2) mega(Params p) {
;     ...
;     for (int phx = ph_lo; phx < ph_hi + REP_N; ++phx) {
;         const int ph = phx <= REP_PH ? phx : (phx <= REP_PH + REP_N ? REP_PH : phx - REP_N);
;         int z = 0; asm volatile("" : "+s"(z));
;         asm volatile("" : "+s"(pp));
;         Params q;
; #pragma unroll
;         for (int i = 0; i < 22; ++i) q.in[i] = pp->in[i];
;         q.out = pp->out; q.ws = pp->ws; q.ph_lo = 0; q.ph_hi = 0;
;         const int tid = (int)threadIdx.x + z;
;         const int l = ph / NPH, s = ph % NPH;
;         if (s == 0) conv_phase(lds, q, l, tid);
;         else if (s == 1) { if (l == 0) { modred(q, tid); if (ph_hi > 1000) grid.sync(); xcd_barrier(xbar); } norm_phase(q, l, tid); }
;         else if (s == 2) {
;             pg8::Gemm g{(const bf16_t*)(q.ws + WS_H), (const bf16_t*)(q.ws + WS_WIN), MT, NPAD, 2048, 2048, 2048};
;             pg8::StaticOrder S; S.init(MT, NPAD, (int)gridDim.x, (int)blockIdx.x);
;             Epi1 E{(bf16_t*)(q.ws + WS_QKVA), (bf16_t*)(q.ws + WS_GA), (bf16_t*)(q.ws + WS_QB), (bf16_t*)(q.ws + WS_GB), (bf16_t*)(q.ws + WS_MA), (bf16_t*)(q.ws + WS_MB),
;                    (float*)(q.ws + WS_BG), q.in[13] + l * 8, q.in[14] + l * 8};
;             pg8::gemm_phase<Epi1>((LAS unsigned char*)lds, g, S, E, tid);
;         }
;         else if (s == 3) prep_phase(lds, q, l, tid);
;         else if (s == 4) attn_phase(lds, q, l, tid);
;         else if (s == 5 || s == 7) g1_phase(lds, q, l, s == 7 ? 1 : 0, tid);
;         else if (s == 6 || s == 8) g2_phase(lds, q, l, s == 8 ? 1 : 0, tid);
;         else if (s == 9) fin_phase(q, l, tid);
;         else if (s == 10) {
;             sample_gemm<2>(q, l, tid);
;             pg8::Gemm g{(const bf16_t*)(q.ws + WS_H), (const bf16_t*)(q.ws + WS_WP), MP, 2048, 1024, 2048, 2048};
;             pg8::StaticOrder S; S.init(MP, 2048, (int)gridDim.x, (int)blockIdx.x, 2);
;             Epi2 E{(const bf16_t*)(q.ws + WS_MA), (const bf16_t*)(q.ws + WS_MB), (bf16_t*)(q.ws + WS_MERGED)};
;             pg8::gemm_phase<Epi2>((LAS unsigned char*)lds, g, S, E, tid);
;         }
;         else {
;             sample_gemm<3>(q, l, tid);
;             pg8::Gemm g{(const bf16_t*)(q.ws + WS_MERGED), (const bf16_t*)(q.ws + WS_WO), MP, 2048, 2048, 2048, 2048};
;             pg8::StaticOrder S; S.init(MP, 2048, (int)gridDim.x, (int)blockIdx.x);
.LBB0_831:
	s_add_i32 s82, s82, 1
	v_readlane_b32 s20, v247, 62
	v_readlane_b32 s24, v246, 0
	v_readlane_b32 s26, v246, 2
	v_readlane_b32 s28, v246, 4
	v_readlane_b32 s30, v246, 6
	v_readlane_b32 s34, v246, 8
	v_readlane_b32 s36, v246, 10
	v_readlane_b32 s40, v246, 12
	v_readlane_b32 s42, v246, 14
	v_readlane_b32 s44, v246, 16
	v_readlane_b32 s46, v246, 18
	v_readlane_b32 s48, v246, 20
	v_readlane_b32 s50, v246, 22
	v_readlane_b32 s84, v246, 24
	s_cmp_ge_i32 s82, s83
	s_mov_b64 s[2:3], -1
	v_readlane_b32 s21, v247, 63
	v_readlane_b32 s25, v246, 1
	v_readlane_b32 s27, v246, 3
	v_readlane_b32 s29, v246, 5
	v_readlane_b32 s31, v246, 7
	v_readlane_b32 s35, v246, 9
	v_readlane_b32 s37, v246, 11
	v_readlane_b32 s41, v246, 13
	v_readlane_b32 s43, v246, 15
	v_readlane_b32 s45, v246, 17
	v_readlane_b32 s47, v246, 19
	v_readlane_b32 s49, v246, 21
	v_readlane_b32 s51, v246, 23
	v_readlane_b32 s85, v246, 25
	v_readlane_b32 s1, v246, 26
	s_cbranch_scc1 .Lnb_go
	s_cmp_eq_u32 s82, 13
	s_cbranch_scc0 .LBB0_832
	s_mov_b64 s[2:3], 0
.Lnb_go:
	s_getpc_b64 s[98:99]
